# static priority raise for the younger half: s_setprio 3 on the prompt-scan loader waves (4-7) so their LDS-DMA issues promptly after each chunk barrier
# speedup vs baseline: 1.0018x; 1.0018x over previous
; #define SCAN_BAR() asm volatile("s_barrier" ::: "memory")
; #define SCAN_ISSUE(ch) do { const int _c = (ch) < nch ? (ch) : nch - 1; const unsigned char* _g = sb + (size_t)_c * (32 * 12288); const int _slot = (ch) & 1; \
;         _Pragma("unroll") for (int _i = 0; _i < 12; ++_i) __builtin_amdgcn_global_load_lds((const unsigned*)(_g + goff[_i]), (LAS unsigned*)(C.lds + _slot * SLOT_B + (lw * 12 + _i) * 1024), 16, 0, 0); } while (0)
; __device__ __forceinline__ void scan_unit(const Ctx& C0, const float* scn, int T, int quarter, const float* S0, float* Sout, unsigned char* obase, int mode) {
;     ...
;     const bool comp = C.wave < 4;
;     const int q = C.lane & 15, rr = C.lane >> 4, rl = (C.wave & 3) * 4 + rr, irow = quarter * 16 + rl;
;     const int nch = T / 32;
;     __syncthreads();
;     if (!comp) {
;         const int lw = C.wave - 4;
;         unsigned goff[12];
; #pragma unroll
;         for (int i = 0; i < 12; ++i) { const int x = (lw * 12 + i) * 1024 + C.lane * 16; goff[i] = (unsigned)((x / 1536) * 12288 + (x % 1536)); }
;         const unsigned char* sb = (const unsigned char*)scn;
;     ...
;         if (mode != 1) SCAN_ISSUE(0);
;         asm volatile("s_waitcnt vmcnt(0)" ::: "memory");
;         SCAN_BAR();
.LBB0_677:
	s_andn2_b64 vcc, exec, s[0:1]
	s_mov_b64 s[52:53], 0
	s_cbranch_vccnz .LBB0_1182
	s_cmpk_gt_i32 s72, 0x7f
	s_cselect_b64 s[52:53], -1, 0
	s_mov_b64 s[0:1], -1
	s_and_b64 vcc, exec, s[52:53]
	s_cbranch_vccnz .LBB0_688
	s_lshl_b32 s38, s72, 2
	v_readlane_b32 s24, v253, 4
	s_and_b32 s0, s38, 28
	s_ashr_i32 s1, s72, 5
	v_readlane_b32 s25, v253, 5
	s_add_i32 s0, s0, s1
	v_mov_b32_e32 v52, v185
	s_ashr_i32 s3, s0, 3
	s_and_b32 s2, s0, 7
	s_mov_b32 s0, s72
	s_mov_b32 s1, s76
	v_readfirstlane_b32 s8, v52
	s_ashr_i32 s9, s8, 6
	v_and_b32_e32 v53, 63, v52
	s_cmp_lt_i32 s9, 4
	s_mov_b64 s[0:1], -1
	s_barrier
	s_cbranch_scc1 .LBB0_683
	s_setprio 3
	s_mul_i32 s13, s3, 0x6000000
	s_mul_hi_i32 s11, s3, 0x6000000
	s_add_u32 s0, s24, s13
	s_addc_u32 s1, s25, s11
	s_mul_i32 s10, s2, 0x600
	s_add_u32 s0, s0, s10
	s_addc_u32 s1, s1, 0
	s_add_u32 s0, s0, 0x256d7900
	s_mul_i32 s10, s9, 0x3000
	s_addc_u32 s1, s1, 0
	s_waitcnt lgkmcnt(0)
	v_lshlrev_b32_e32 v3, 4, v53
	s_add_i32 s12, s10, 0xffff4000
	v_or_b32_e32 v46, s12, v3
	s_mov_b32 s26, 0xaaaaaaab
	v_mul_hi_u32 v0, v46, s26
	v_lshrrev_b32_e32 v47, 10, v0
	v_mul_u32_u24_e32 v48, 0x600, v47
	s_add_i32 s14, s10, 0xffff4400
	v_mul_u32_u24_e32 v0, 0x3000, v47
	v_sub_u32_e32 v2, v46, v48
	v_or_b32_e32 v44, s14, v3
	v_or_b32_e32 v0, v0, v2
	v_mul_hi_u32 v2, v44, s26
	v_lshrrev_b32_e32 v45, 10, v2
	v_mul_u32_u24_e32 v49, 0x600, v45
	s_add_i32 s15, s10, 0xffff4800
	v_mul_u32_u24_e32 v2, 0x3000, v45
	v_sub_u32_e32 v4, v44, v49
	v_or_b32_e32 v42, s15, v3
	v_or_b32_e32 v2, v2, v4
	v_mul_hi_u32 v4, v42, s26
	v_lshrrev_b32_e32 v43, 10, v4
	v_mul_u32_u24_e32 v50, 0x600, v43
	s_add_i32 s16, s10, 0xffff4c00
	v_mul_u32_u24_e32 v4, 0x3000, v43
	v_sub_u32_e32 v5, v42, v50
	v_or_b32_e32 v40, s16, v3
	v_or_b32_e32 v4, v4, v5
	v_mul_hi_u32 v5, v40, s26
	v_lshrrev_b32_e32 v41, 10, v5
	v_mul_u32_u24_e32 v51, 0x600, v41
	s_add_i32 s18, s10, 0xffff5000
	v_mul_u32_u24_e32 v5, 0x3000, v41
	v_sub_u32_e32 v6, v40, v51
	v_or_b32_e32 v38, s18, v3
	v_or_b32_e32 v6, v5, v6
	v_mul_hi_u32 v5, v38, s26
	v_lshrrev_b32_e32 v39, 10, v5
	v_mul_u32_u24_e32 v54, 0x600, v39
	s_add_i32 s19, s10, 0xffff5400
	v_mul_u32_u24_e32 v5, 0x3000, v39
	v_sub_u32_e32 v7, v38, v54
	v_or_b32_e32 v36, s19, v3
	v_or_b32_e32 v8, v5, v7
	v_mul_hi_u32 v5, v36, s26
	v_lshrrev_b32_e32 v37, 10, v5
	v_mul_u32_u24_e32 v55, 0x600, v37
	s_add_i32 s30, s10, 0xffff5800
	v_mul_u32_u24_e32 v5, 0x3000, v37
	v_sub_u32_e32 v7, v36, v55
	v_or_b32_e32 v34, s30, v3
	v_or_b32_e32 v10, v5, v7
	v_mul_hi_u32 v5, v34, s26
	v_lshrrev_b32_e32 v35, 10, v5
	v_mul_u32_u24_e32 v56, 0x600, v35
	s_add_i32 s31, s10, 0xffff5c00
	v_mul_u32_u24_e32 v5, 0x3000, v35
	v_sub_u32_e32 v7, v34, v56
	v_or_b32_e32 v32, s31, v3
	v_or_b32_e32 v12, v5, v7
	v_mul_hi_u32 v5, v32, s26
	v_lshrrev_b32_e32 v33, 10, v5
	v_mul_u32_u24_e32 v57, 0x600, v33
	s_add_i32 s36, s10, 0xffff6000
	v_mul_u32_u24_e32 v5, 0x3000, v33
	v_sub_u32_e32 v7, v32, v57
	v_or_b32_e32 v30, s36, v3
	v_or_b32_e32 v14, v5, v7
	v_mul_hi_u32 v5, v30, s26
	v_lshrrev_b32_e32 v31, 10, v5
	s_add_i32 s12, s12, 0
	v_mul_u32_u24_e32 v58, 0x600, v31
	s_add_i32 s37, s10, 0xffff6400
	s_mov_b32 m0, s12
	s_add_i32 s14, s14, 0
	v_mul_u32_u24_e32 v5, 0x3000, v31
	v_sub_u32_e32 v7, v30, v58
	v_or_b32_e32 v28, s37, v3
	global_load_lds_dwordx4 v0, s[0:1]
	s_mov_b32 m0, s14
	s_add_i32 s15, s15, 0
	v_or_b32_e32 v16, v5, v7
	v_mul_hi_u32 v5, v28, s26
	global_load_lds_dwordx4 v2, s[0:1]
	s_mov_b32 m0, s15
	s_add_i32 s16, s16, 0
	v_lshrrev_b32_e32 v29, 10, v5
	global_load_lds_dwordx4 v4, s[0:1]
	s_mov_b32 m0, s16
	s_add_i32 s18, s18, 0
	v_mul_u32_u24_e32 v59, 0x600, v29
	s_add_i32 s39, s10, 0xffff6800
	global_load_lds_dwordx4 v6, s[0:1]
	s_mov_b32 m0, s18
	s_add_i32 s19, s19, 0
	v_mul_u32_u24_e32 v5, 0x3000, v29
	v_sub_u32_e32 v7, v28, v59
	v_or_b32_e32 v26, s39, v3
	s_add_i32 s41, s10, 0xffff6c00
	global_load_lds_dwordx4 v8, s[0:1]
	s_mov_b32 m0, s19
	s_add_i32 s30, s30, 0
	v_or_b32_e32 v18, v5, v7
	v_mul_hi_u32 v5, v26, s26
	v_or_b32_e32 v24, s41, v3
	global_load_lds_dwordx4 v10, s[0:1]
	s_mov_b32 m0, s30
	s_add_i32 s31, s31, 0
	v_lshrrev_b32_e32 v27, 10, v5
	v_mul_hi_u32 v3, v24, s26
	global_load_lds_dwordx4 v12, s[0:1]
	s_mov_b32 m0, s31
	s_add_i32 s36, s36, 0
	v_mul_u32_u24_e32 v60, 0x600, v27
	v_lshrrev_b32_e32 v25, 10, v3
	global_load_lds_dwordx4 v14, s[0:1]
	s_mov_b32 m0, s36
	s_add_i32 s37, s37, 0
	v_mul_u32_u24_e32 v5, 0x3000, v27
	v_sub_u32_e32 v7, v26, v60
	v_mul_u32_u24_e32 v61, 0x600, v25
	global_load_lds_dwordx4 v16, s[0:1]
	s_mov_b32 m0, s37
	s_add_i32 s40, s39, 0
	v_or_b32_e32 v20, v5, v7
	v_mul_u32_u24_e32 v3, 0x3000, v25
	v_sub_u32_e32 v5, v24, v61
	global_load_lds_dwordx4 v18, s[0:1]
	s_mov_b32 m0, s40
	s_add_i32 s41, s41, 0
	v_or_b32_e32 v22, v3, v5
	global_load_lds_dwordx4 v20, s[0:1]
	s_mov_b32 m0, s41
	s_lshr_b32 s39, s72, 5
	global_load_lds_dwordx4 v22, s[0:1]
	s_add_i32 s38, s38, s39
	s_and_b32 s38, s38, 7
	s_mulk_i32 s38, 0x600
	s_waitcnt vmcnt(0)
	s_or_b32 s13, s13, s38
	s_movk_i32 s26, 0x3000
	s_barrier
	v_mad_u32_u24 v24, v25, s26, v24
	s_add_u32 s24, s24, s13
	v_mad_u32_u24 v26, v27, s26, v26
	v_mad_u32_u24 v28, v29, s26, v28
	v_mad_u32_u24 v30, v31, s26, v30
	v_mad_u32_u24 v32, v33, s26, v32
	v_mad_u32_u24 v34, v35, s26, v34
	v_mad_u32_u24 v36, v37, s26, v36
	v_mad_u32_u24 v38, v39, s26, v38
	v_mad_u32_u24 v40, v41, s26, v40
	v_mad_u32_u24 v42, v43, s26, v42
	v_mad_u32_u24 v44, v45, s26, v44
	v_mad_u32_u24 v46, v47, s26, v46
	v_sub_u32_e32 v24, v24, v61
	v_mov_b32_e32 v25, v1
	s_addc_u32 s25, s25, s11
	v_sub_u32_e32 v26, v26, v60
	v_mov_b32_e32 v27, v1
	v_sub_u32_e32 v28, v28, v59
	v_mov_b32_e32 v29, v1
	v_sub_u32_e32 v30, v30, v58
	v_mov_b32_e32 v31, v1
	v_sub_u32_e32 v32, v32, v57
	v_mov_b32_e32 v33, v1
	v_sub_u32_e32 v34, v34, v56
	v_mov_b32_e32 v35, v1
	v_sub_u32_e32 v36, v36, v55
	v_mov_b32_e32 v37, v1
	v_sub_u32_e32 v38, v38, v54
	v_mov_b32_e32 v39, v1
	v_sub_u32_e32 v40, v40, v51
	v_mov_b32_e32 v41, v1
	v_sub_u32_e32 v42, v42, v50
	v_mov_b32_e32 v43, v1
	v_sub_u32_e32 v44, v44, v49
	v_mov_b32_e32 v45, v1
	v_sub_u32_e32 v46, v46, v48
	v_mov_b32_e32 v47, v1
	s_mov_b32 s42, 4
	v_mov_b32_e32 v3, v1
	v_mov_b32_e32 v5, v1
	v_mov_b32_e32 v7, v1
	v_mov_b32_e32 v9, v1
	v_mov_b32_e32 v11, v1
	v_mov_b32_e32 v13, v1
	v_mov_b32_e32 v15, v1
	v_mov_b32_e32 v17, v1
	v_mov_b32_e32 v19, v1
	v_mov_b32_e32 v21, v1
	v_mov_b32_e32 v23, v1
	v_lshl_add_u64 v[24:25], s[24:25], 0, v[24:25]
	v_lshl_add_u64 v[26:27], s[24:25], 0, v[26:27]
	v_lshl_add_u64 v[28:29], s[24:25], 0, v[28:29]
	v_lshl_add_u64 v[30:31], s[24:25], 0, v[30:31]
	v_lshl_add_u64 v[32:33], s[24:25], 0, v[32:33]
	v_lshl_add_u64 v[34:35], s[24:25], 0, v[34:35]
	v_lshl_add_u64 v[36:37], s[24:25], 0, v[36:37]
	v_lshl_add_u64 v[38:39], s[24:25], 0, v[38:39]
	v_lshl_add_u64 v[40:41], s[24:25], 0, v[40:41]
	v_lshl_add_u64 v[42:43], s[24:25], 0, v[42:43]
	v_lshl_add_u64 v[44:45], s[24:25], 0, v[44:45]
	v_lshl_add_u64 v[46:47], s[24:25], 0, v[46:47]
	s_mov_b64 s[24:25], 0
	s_mov_b64 s[26:27], 0x25737900
	s_mov_b64 s[58:59], 0x25797900
	s_mov_b64 s[60:61], 0x257f7900
; #define SCAN_BAR() asm volatile("s_barrier" ::: "memory")
; #define SCAN_ISSUE(ch) do { const int _c = (ch) < nch ? (ch) : nch - 1; const unsigned char* _g = sb + (size_t)_c * (32 * 12288); const int _slot = (ch) & 1; \
;         _Pragma("unroll") for (int _i = 0; _i < 12; ++_i) __builtin_amdgcn_global_load_lds((const unsigned*)(_g + goff[_i]), (LAS unsigned*)(C.lds + _slot * SLOT_B + (lw * 12 + _i) * 1024), 16, 0, 0); } while (0)
; __device__ __forceinline__ void scan_unit(const Ctx& C0, const float* scn, int T, int quarter, const float* S0, float* Sout, unsigned char* obase, int mode) {
;     ...
;         if (mode != 1) SCAN_ISSUE(0);
;         asm volatile("s_waitcnt vmcnt(0)" ::: "memory");
;         SCAN_BAR();
;         for (int k = 0; k < nch; ++k) {
;             if (mode != 1) SCAN_ISSUE(k + 1);
;             asm volatile("s_waitcnt vmcnt(0)" ::: "memory");
;             SCAN_BAR();
;         }
.LBB0_681:
	v_lshl_add_u64 v[48:49], v[46:47], 0, s[24:25]
	s_add_i32 s38, s10, 0
	v_lshl_add_u64 v[50:51], v[48:49], 0, s[26:27]
	s_mov_b32 m0, s38
	s_add_i32 s39, s38, 0x400
	global_load_lds_dwordx4 v[50:51], off
	v_lshl_add_u64 v[50:51], v[44:45], 0, s[24:25]
	v_lshl_add_u64 v[54:55], v[50:51], 0, s[26:27]
	s_mov_b32 m0, s39
	s_add_i32 s43, s38, 0x800
	global_load_lds_dwordx4 v[54:55], off
	v_lshl_add_u64 v[54:55], v[42:43], 0, s[24:25]
	v_lshl_add_u64 v[56:57], v[54:55], 0, s[26:27]
	s_mov_b32 m0, s43
	s_add_i32 s44, s38, 0xc00
	global_load_lds_dwordx4 v[56:57], off
	v_lshl_add_u64 v[56:57], v[40:41], 0, s[24:25]
	v_lshl_add_u64 v[58:59], v[56:57], 0, s[26:27]
	s_mov_b32 m0, s44
	s_add_i32 s45, s38, 0x1000
	global_load_lds_dwordx4 v[58:59], off
	v_lshl_add_u64 v[58:59], v[38:39], 0, s[24:25]
	v_lshl_add_u64 v[60:61], v[58:59], 0, s[26:27]
	s_mov_b32 m0, s45
	s_add_i32 s11, s38, 0x1400
	global_load_lds_dwordx4 v[60:61], off
	v_lshl_add_u64 v[60:61], v[36:37], 0, s[24:25]
	v_lshl_add_u64 v[62:63], v[60:61], 0, s[26:27]
	s_mov_b32 m0, s11
	s_add_i32 s13, s38, 0x1800
	global_load_lds_dwordx4 v[62:63], off
	v_lshl_add_u64 v[62:63], v[34:35], 0, s[24:25]
	v_lshl_add_u64 v[64:65], v[62:63], 0, s[26:27]
	s_mov_b32 m0, s13
	s_add_i32 s46, s38, 0x1c00
	global_load_lds_dwordx4 v[64:65], off
	v_lshl_add_u64 v[64:65], v[32:33], 0, s[24:25]
	v_lshl_add_u64 v[66:67], v[64:65], 0, s[26:27]
	s_mov_b32 m0, s46
	s_add_i32 s47, s38, 0x2000
	global_load_lds_dwordx4 v[66:67], off
	v_lshl_add_u64 v[66:67], v[30:31], 0, s[24:25]
	v_lshl_add_u64 v[68:69], v[66:67], 0, s[26:27]
	s_mov_b32 m0, s47
	s_add_i32 s54, s38, 0x2400
	global_load_lds_dwordx4 v[68:69], off
	v_lshl_add_u64 v[68:69], v[28:29], 0, s[24:25]
	v_lshl_add_u64 v[70:71], v[68:69], 0, s[26:27]
	s_mov_b32 m0, s54
	s_add_i32 s55, s38, 0x2800
	global_load_lds_dwordx4 v[70:71], off
	v_lshl_add_u64 v[70:71], v[26:27], 0, s[24:25]
	v_lshl_add_u64 v[72:73], v[70:71], 0, s[26:27]
	s_mov_b32 m0, s55
	s_add_i32 s56, s38, 0x2c00
	global_load_lds_dwordx4 v[72:73], off
	v_lshl_add_u64 v[72:73], v[24:25], 0, s[24:25]
	v_lshl_add_u64 v[74:75], v[72:73], 0, s[26:27]
	s_mov_b32 m0, s56
	s_nop 0
	global_load_lds_dwordx4 v[74:75], off
	s_waitcnt vmcnt(0)
	s_barrier
	v_lshl_add_u64 v[74:75], v[48:49], 0, s[58:59]
	s_mov_b32 m0, s12
	v_lshl_add_u64 v[48:49], v[48:49], 0, s[60:61]
	global_load_lds_dwordx4 v[74:75], off
	v_lshl_add_u64 v[74:75], v[50:51], 0, s[58:59]
	s_mov_b32 m0, s14
	s_nop 0
	global_load_lds_dwordx4 v[74:75], off
	v_lshl_add_u64 v[74:75], v[54:55], 0, s[58:59]
	s_mov_b32 m0, s15
	s_nop 0
	global_load_lds_dwordx4 v[74:75], off
	v_lshl_add_u64 v[74:75], v[56:57], 0, s[58:59]
	s_mov_b32 m0, s16
	s_nop 0
	global_load_lds_dwordx4 v[74:75], off
	v_lshl_add_u64 v[74:75], v[58:59], 0, s[58:59]
	s_mov_b32 m0, s18
	s_nop 0
	global_load_lds_dwordx4 v[74:75], off
	v_lshl_add_u64 v[74:75], v[60:61], 0, s[58:59]
	s_mov_b32 m0, s19
	s_nop 0
	global_load_lds_dwordx4 v[74:75], off
	v_lshl_add_u64 v[74:75], v[62:63], 0, s[58:59]
	s_mov_b32 m0, s30
	s_nop 0
	global_load_lds_dwordx4 v[74:75], off
	v_lshl_add_u64 v[74:75], v[64:65], 0, s[58:59]
	s_mov_b32 m0, s31
	s_nop 0
	global_load_lds_dwordx4 v[74:75], off
	v_lshl_add_u64 v[74:75], v[66:67], 0, s[58:59]
	s_mov_b32 m0, s36
	s_nop 0
	global_load_lds_dwordx4 v[74:75], off
	v_lshl_add_u64 v[74:75], v[68:69], 0, s[58:59]
	s_mov_b32 m0, s37
	s_nop 0
	global_load_lds_dwordx4 v[74:75], off
	v_lshl_add_u64 v[74:75], v[70:71], 0, s[58:59]
	s_mov_b32 m0, s40
	s_nop 0
	global_load_lds_dwordx4 v[74:75], off
	v_lshl_add_u64 v[74:75], v[72:73], 0, s[58:59]
	s_mov_b32 m0, s41
	s_nop 0
	global_load_lds_dwordx4 v[74:75], off
	s_waitcnt vmcnt(0)
	s_barrier
	s_mov_b32 m0, s38
	s_nop 0
	global_load_lds_dwordx4 v[48:49], off
	v_lshl_add_u64 v[48:49], v[50:51], 0, s[60:61]
	s_mov_b32 m0, s39
	s_nop 0
	global_load_lds_dwordx4 v[48:49], off
	v_lshl_add_u64 v[48:49], v[54:55], 0, s[60:61]
	s_mov_b32 m0, s43
	s_nop 0
	global_load_lds_dwordx4 v[48:49], off
	v_lshl_add_u64 v[48:49], v[56:57], 0, s[60:61]
	s_mov_b32 m0, s44
	s_nop 0
	global_load_lds_dwordx4 v[48:49], off
	v_lshl_add_u64 v[48:49], v[58:59], 0, s[60:61]
	s_mov_b32 m0, s45
	s_nop 0
	global_load_lds_dwordx4 v[48:49], off
	v_lshl_add_u64 v[48:49], v[60:61], 0, s[60:61]
	s_mov_b32 m0, s11
	s_min_u32 s11, s42, 0xff
	global_load_lds_dwordx4 v[48:49], off
	v_lshl_add_u64 v[48:49], v[62:63], 0, s[60:61]
	s_mov_b32 m0, s13
	s_mul_i32 s11, s11, 0x60000
	global_load_lds_dwordx4 v[48:49], off
	v_lshl_add_u64 v[48:49], v[64:65], 0, s[60:61]
	s_mov_b32 m0, s46
	s_add_u32 s38, s0, s11
	global_load_lds_dwordx4 v[48:49], off
	v_lshl_add_u64 v[48:49], v[66:67], 0, s[60:61]
	s_mov_b32 m0, s47
	s_addc_u32 s39, s1, 0
	global_load_lds_dwordx4 v[48:49], off
	v_lshl_add_u64 v[48:49], v[68:69], 0, s[60:61]
	s_mov_b32 m0, s54
	s_add_u32 s24, s24, 0x180000
	global_load_lds_dwordx4 v[48:49], off
	v_lshl_add_u64 v[48:49], v[70:71], 0, s[60:61]
	s_mov_b32 m0, s55
	s_addc_u32 s25, s25, 0
	global_load_lds_dwordx4 v[48:49], off
	v_lshl_add_u64 v[48:49], v[72:73], 0, s[60:61]
	s_mov_b32 m0, s56
	s_add_i32 s42, s42, 4
	global_load_lds_dwordx4 v[48:49], off
	s_waitcnt vmcnt(0)
	s_barrier
	v_lshl_add_u64 v[48:49], s[38:39], 0, v[0:1]
	s_mov_b32 m0, s12
	s_cmp_eq_u32 s24, 0x6000000
	global_load_lds_dwordx4 v[48:49], off
	v_lshl_add_u64 v[48:49], s[38:39], 0, v[2:3]
	s_mov_b32 m0, s14
	s_nop 0
	global_load_lds_dwordx4 v[48:49], off
	v_lshl_add_u64 v[48:49], s[38:39], 0, v[4:5]
	s_mov_b32 m0, s15
	s_nop 0
	global_load_lds_dwordx4 v[48:49], off
	v_lshl_add_u64 v[48:49], s[38:39], 0, v[6:7]
	s_mov_b32 m0, s16
	s_nop 0
	global_load_lds_dwordx4 v[48:49], off
	v_lshl_add_u64 v[48:49], s[38:39], 0, v[8:9]
	s_mov_b32 m0, s18
	s_nop 0
	global_load_lds_dwordx4 v[48:49], off
	v_lshl_add_u64 v[48:49], s[38:39], 0, v[10:11]
	s_mov_b32 m0, s19
	s_nop 0
	global_load_lds_dwordx4 v[48:49], off
	v_lshl_add_u64 v[48:49], s[38:39], 0, v[12:13]
	s_mov_b32 m0, s30
	s_nop 0
	global_load_lds_dwordx4 v[48:49], off
	v_lshl_add_u64 v[48:49], s[38:39], 0, v[14:15]
	s_mov_b32 m0, s31
	s_nop 0
	global_load_lds_dwordx4 v[48:49], off
	v_lshl_add_u64 v[48:49], s[38:39], 0, v[16:17]
	s_mov_b32 m0, s36
	s_nop 0
	global_load_lds_dwordx4 v[48:49], off
	v_lshl_add_u64 v[48:49], s[38:39], 0, v[18:19]
	s_mov_b32 m0, s37
	s_nop 0
	global_load_lds_dwordx4 v[48:49], off
	v_lshl_add_u64 v[48:49], s[38:39], 0, v[20:21]
	s_mov_b32 m0, s40
	s_nop 0
	global_load_lds_dwordx4 v[48:49], off
	v_lshl_add_u64 v[48:49], s[38:39], 0, v[22:23]
	s_mov_b32 m0, s41
	s_nop 0
	global_load_lds_dwordx4 v[48:49], off
	s_waitcnt vmcnt(0)
	s_barrier
	s_cbranch_scc0 .LBB0_681
	s_setprio 0
	s_mov_b64 s[0:1], 0
